# second cache_shift copy loop also unrolled 4x
# speedup vs baseline: 1.0089x; 1.0006x over previous
; DI void cache_shift(ArgsP a, int gt, int NT) {
;     ...
;     for (int i = gt; i < 4 * 128 * 11 * 128; i += NT) { const int c4 = i & 127, j = (i >> 7) % 11, lb = (i >> 7) / 11;
;         *(f32x4*)(a->out + OFF_PS + ((size_t)lb * 15 + j) * 512 + c4 * 4) = *(const f32x4*)(a->in[4] + ((size_t)lb * 15 + j + 4) * 512 + c4 * 4); }
.LBB0_181:
	s_or_b64 exec, exec, s[2:3]
	s_mov_b32 s2, 0xb0000
	v_cmp_gt_i32_e32 vcc, s2, v0
	s_and_saveexec_b64 s[2:3], vcc
	s_mov_b32 s9, 0x2e8ba2e9
	s_mov_b32 s12, 0xaffff
	s_cbranch_execz .LBB0_184
	s_add_u32 s4, s24, 0x8770000
	s_addc_u32 s5, s25, 0
	s_lshl_b32 s8, s51, 11
	s_add_i32 s8, s8, 0xfffd0000
	s_mov_b64 s[6:7], 0
	v_mov_b32_e32 v13, v0
.LBB0_183:
	s_load_dwordx2 s[10:11], s[34:35], 0x20
	v_and_b32_e32 v3, 0x1fc, v1
	v_lshlrev_b32_e32 v96, 2, v3
	s_waitcnt lgkmcnt(0)
	s_add_u32 s10, s10, 0x2000
	s_addc_u32 s11, s11, 0
	v_ashrrev_i32_e32 v2, 7, v0
	v_mul_hi_i32 v4, v2, s9
	v_lshrrev_b32_e32 v3, 31, v4
	v_ashrrev_i32_e32 v4, 1, v4
	v_add_u32_e32 v3, v4, v3
	v_mul_lo_u32 v4, v3, 11
	v_sub_u32_e32 v2, v2, v4
	v_mad_u64_u32 v[2:3], vcc, v3, 15, v[2:3]
	v_ashrrev_i32_e32 v3, 31, v2
	v_lshlrev_b64 v[2:3], 11, v[2:3]
	v_lshl_add_u64 v[16:17], v[2:3], 0, v[96:97]
	v_lshl_add_u64 v[4:5], s[10:11], 0, v[16:17]
	global_load_dwordx4 v[24:27], v[4:5], off
	v_add_u32_e32 v12, s14, v0
	v_cmp_ge_i32_e32 vcc, s12, v12
	s_and_b64 exec, exec, vcc
	v_ashrrev_i32_e32 v2, 7, v12
	v_mul_hi_i32 v4, v2, s9
	v_lshrrev_b32_e32 v3, 31, v4
	v_ashrrev_i32_e32 v4, 1, v4
	v_add_u32_e32 v3, v4, v3
	v_mul_lo_u32 v4, v3, 11
	v_sub_u32_e32 v2, v2, v4
	v_mad_u64_u32 v[2:3], vcc, v3, 15, v[2:3]
	v_ashrrev_i32_e32 v3, 31, v2
	v_lshlrev_b64 v[2:3], 11, v[2:3]
	v_lshl_add_u64 v[18:19], v[2:3], 0, v[96:97]
	v_lshl_add_u64 v[4:5], s[10:11], 0, v[18:19]
	global_load_dwordx4 v[28:31], v[4:5], off
	v_add_u32_e32 v12, s14, v12
	v_cmp_ge_i32_e32 vcc, s12, v12
	s_and_b64 exec, exec, vcc
	v_ashrrev_i32_e32 v2, 7, v12
	v_mul_hi_i32 v4, v2, s9
	v_lshrrev_b32_e32 v3, 31, v4
	v_ashrrev_i32_e32 v4, 1, v4
	v_add_u32_e32 v3, v4, v3
	v_mul_lo_u32 v4, v3, 11
	v_sub_u32_e32 v2, v2, v4
	v_mad_u64_u32 v[2:3], vcc, v3, 15, v[2:3]
	v_ashrrev_i32_e32 v3, 31, v2
	v_lshlrev_b64 v[2:3], 11, v[2:3]
	v_lshl_add_u64 v[20:21], v[2:3], 0, v[96:97]
	v_lshl_add_u64 v[4:5], s[10:11], 0, v[20:21]
	global_load_dwordx4 v[32:35], v[4:5], off
	v_add_u32_e32 v12, s14, v12
	v_cmp_ge_i32_e32 vcc, s12, v12
	s_and_b64 exec, exec, vcc
	v_ashrrev_i32_e32 v2, 7, v12
	v_mul_hi_i32 v4, v2, s9
	v_lshrrev_b32_e32 v3, 31, v4
	v_ashrrev_i32_e32 v4, 1, v4
	v_add_u32_e32 v3, v4, v3
	v_mul_lo_u32 v4, v3, 11
	v_sub_u32_e32 v2, v2, v4
	v_mad_u64_u32 v[2:3], vcc, v3, 15, v[2:3]
	v_ashrrev_i32_e32 v3, 31, v2
	v_lshlrev_b64 v[2:3], 11, v[2:3]
	v_lshl_add_u64 v[22:23], v[2:3], 0, v[96:97]
	v_lshl_add_u64 v[4:5], s[10:11], 0, v[22:23]
	global_load_dwordx4 v[36:39], v[4:5], off
	s_waitcnt vmcnt(0)
	s_mov_b64 exec, s[2:3]
	v_cmp_ge_i32_e32 vcc, s12, v13
	s_and_b64 exec, exec, vcc
	s_andn2_b64 exec, exec, s[6:7]
	v_lshl_add_u64 v[4:5], s[4:5], 0, v[16:17]
	global_store_dwordx4 v[4:5], v[24:27], off
	v_add_u32_e32 v12, s14, v0
	v_cmp_ge_i32_e32 vcc, s12, v12
	s_and_b64 exec, exec, vcc
	v_lshl_add_u64 v[4:5], s[4:5], 0, v[18:19]
	global_store_dwordx4 v[4:5], v[28:31], off
	v_add_u32_e32 v12, s14, v12
	v_cmp_ge_i32_e32 vcc, s12, v12
	s_and_b64 exec, exec, vcc
	v_lshl_add_u64 v[4:5], s[4:5], 0, v[20:21]
	global_store_dwordx4 v[4:5], v[32:35], off
	v_add_u32_e32 v12, s14, v12
	v_cmp_ge_i32_e32 vcc, s12, v12
	s_and_b64 exec, exec, vcc
	v_lshl_add_u64 v[4:5], s[4:5], 0, v[22:23]
	global_store_dwordx4 v[4:5], v[36:39], off
	s_mov_b64 exec, s[2:3]
	v_cmp_ge_i32_e32 vcc, s12, v13
	s_and_b64 exec, exec, vcc
	s_andn2_b64 exec, exec, s[6:7]
	v_lshl_add_u32 v0, s14, 2, v0
	v_cmp_lt_i32_e32 vcc, s12, v0
	s_or_b64 s[6:7], vcc, s[6:7]
	s_andn2_b64 exec, exec, s[6:7]
	s_cbranch_execnz .LBB0_183
